# v39 plus: the once-read q/k/v loads of neighbourhood attention (row LDS-DMA, Q fragments) marked nt
# speedup vs baseline: 1.0023x; 1.0008x over previous
; #define LAS __attribute__((address_space(3)))
; #define LDS_WAIT() asm volatile("s_waitcnt lgkmcnt(0)" ::: "memory")
; #define VM_WAIT() asm volatile("s_waitcnt vmcnt(0)" ::: "memory")
; __device__ __forceinline__ void ph_na_mfma(const Args& a, const Frame& F, int l) {
;     ...
;     const int w = F.wave, qt = w & 3, half = w >> 2, q = lane & 15, g = lane >> 4;
;     const int c0 = 16 * qt, kc0 = (qt == 0) ? 0 : (qt == 1 ? 8 : (qt == 2 ? 24 : 32)), c = c0 + q, cs = min(max(c - 8, 0), 48);
;     const int NIT = (NTOK / 64) * 16; const int i0 = (int)((long)NIT * F.vcu / F.G), i1 = (int)((long)NIT * (F.vcu + 1) / F.G);
;     ...
;     pg8::bf16x8 qn0, qn1;
;     { int s0, R, h, r; NA_ITEM(i0, s0, R, h, r); const bf16* qp = Z + ((size_t)h * NTOK + (s0 + r * 64 + c)) * 64 + 8 * g; qn0 = *(const pg8::bf16x8*)qp; qn1 = *(const pg8::bf16x8*)(qp + 32); }
;     v2u st0, st1, st2, st3; bf16* stp = Y;
;     st0 = st1 = st2 = st3 = (v2u){0u, 0u};
;     int it = i0;
;     while (it < i1) {
;         int s0, R, h, r0; NA_ITEM(it, s0, R, h, r0);
;         const int m = min(R - r0, i1 - it);
;         {
;             const int rs = min(max(r0 - 4, 0), R - 8);
; #pragma unroll
;             for (int i = 0; i < 16; ++i) { const int id = w * 16 + i, t = id >> 6, ri = (id >> 3) & 7, j8 = id & 7, row = rs + ri;
;                 const int colw = 8 * j8 + (lane >> 3);
;                 const bf16* gp = Z + ((size_t)((t ? 32 : 16) + h) * NTOK + (s0 + row * 64 + colw)) * 64 + (((lane & 7) ^ NA_SWZ(colw)) * 8);
;                 glds16_asm(gp, (unsigned)(size_t)(L + (t ? VR : KR) + (row % 9) * 8192 + j8 * 1024)); }
;             if (tid < 465) ((LAS float*)(L + BIAS))[tid] = a.in[I_RPB][((size_t)l * 16 + h) * 465 + tid];
;             VM_WAIT(); LDS_WAIT();
;             __syncthreads();
;         }
;         float ti[4][2][4];
;         { const LAS float* bt = (const LAS float*)(L + BIAS);
; #pragma unroll
;           for (int kk = 0; kk < 4; ++kk)
; #pragma unroll
;               for (int blk = 0; blk < 2; ++blk)
; #pragma unroll
;                   for (int rg = 0; rg < 4; ++rg) { const int col = kc0 + 8 * g + 4 * blk + rg; const int dc = min(max(col - c + 15, 0), 30); const bool valid = (unsigned)(col - cs) < 16u;
;                       ti[kk][blk][rg] = valid ? 8.f * bt[(kk + 4 * half + 3) * 31 + dc] : -INFINITY; } }
.LBB0_284:
	v_and_b32_e32 v1, 15, v10
	s_mov_b32 s6, s22
	v_readlane_b32 s22, v252, 28
	s_and_b32 s0, s0, 15
	s_mul_i32 s82, s0, 0xa000
	v_or_b32_e32 v41, s22, v1
	v_sub_u32_e64 v2, v41, 8 clamp
	v_min_u32_e32 v14, 48, v2
	v_lshl_or_b32 v2, s4, 6, v41
	v_add_u32_e32 v2, s5, v2
	s_waitcnt vmcnt(0) lgkmcnt(0)
	v_ashrrev_i32_e32 v3, 31, v2
	v_lshl_add_u64 v[2:3], v[2:3], 0, s[82:83]
	v_lshlrev_b64 v[2:3], 7, v[2:3]
	v_lshl_add_u64 v[2:3], s[64:65], 0, v[2:3]
	v_and_b32_e32 v12, 48, v10
	v_mov_b32_e32 v13, v191
	v_lshl_add_u64 v[2:3], v[2:3], 0, v[12:13]
	global_load_dwordx4 v[6:9], v[2:3], off offset:64 nt
	s_nop 0
	global_load_dwordx4 v[2:5], v[2:3], off nt
	v_lshl_add_u64 v[90:91], s[64:65], 0, v[12:13]
	v_lshlrev_b32_e32 v12, 1, v10
	v_and_b32_e32 v12, 24, v12
	v_add_u32_e32 v12, s1, v12
	v_and_or_b32 v13, v10, 3, v12
	v_lshrrev_b32_e32 v12, 2, v12
	v_bfe_u32 v16, v10, 4, 2
	v_and_b32_e32 v12, 6, v12
	v_bfe_u32 v21, v10, 1, 1
	v_lshlrev_b32_e32 v190, 3, v16
	v_bitop3_b32 v22, v12, v16, v21 bitop3:0x36
	v_or_b32_e32 v16, 4, v16
	v_bitop3_b32 v12, v12, v16, v21 bitop3:0x36
	v_add_u32_e32 v20, s1, v190
	v_lshlrev_b32_e32 v125, 4, v12
	v_bfe_u32 v12, v10, 2, 2
	v_or_b32_e32 v12, v20, v12
	v_lshlrev_b32_e32 v23, 3, v10
	v_lshlrev_b32_e32 v12, 7, v12
	s_add_i32 s1, 0, 0x12000
	v_and_b32_e32 v23, 8, v23
	v_and_b32_e32 v15, 63, v10
	v_and_b32_e32 v17, 7, v10
	v_lshrrev_b32_e32 v18, 4, v10
	v_add3_u32 v126, s1, v12, v23
	v_readlane_b32 s1, v252, 31
	v_readlane_b32 s20, v249, 9
	v_bfe_u32 v19, v10, 4, 1
	v_or_b32_e32 v12, s1, v15
	v_bitop3_b32 v15, v18, v17, 1 bitop3:0x6c
	v_or_b32_e32 v18, 1, v20
	v_sub_u32_e32 v23, v18, v14
	v_cmp_gt_u32_e64 s[96:97], 16, v23
	v_or_b32_e32 v23, 2, v20
	v_sub_u32_e32 v24, v23, v14
	v_cmp_gt_u32_e64 s[84:85], 16, v24
	v_or_b32_e32 v24, 3, v20
	v_readlane_b32 s21, v249, 10
	v_sub_u32_e32 v25, v24, v14
	v_cmp_gt_u32_e64 s[38:39], 16, v25
	v_lshl_add_u64 v[92:93], s[20:21], 0, v[190:191]
	v_lshlrev_b32_e32 v190, 4, v15
	v_bitop3_b32 v15, v19, v17, 2 bitop3:0x36
	v_or_b32_e32 v25, 4, v20
	v_lshl_add_u64 v[94:95], s[64:65], 0, v[190:191]
	v_lshlrev_b32_e32 v190, 4, v15
	v_bitop3_b32 v15, v19, v17, 4 bitop3:0x36
	v_sub_u32_e32 v26, v25, v14
	v_lshl_add_u64 v[96:97], s[64:65], 0, v[190:191]
	v_lshlrev_b32_e32 v190, 4, v15
	v_bitop3_b32 v15, v19, v17, 6 bitop3:0x36
	v_cmp_gt_u32_e64 s[46:47], 16, v26
	v_or_b32_e32 v26, 5, v20
	v_lshl_add_u64 v[98:99], s[64:65], 0, v[190:191]
	v_lshlrev_b32_e32 v190, 4, v15
	v_sub_u32_e32 v15, v20, v14
	v_sub_u32_e32 v27, v26, v14
	v_lshrrev_b32_e32 v16, 2, v20
	v_cmp_gt_u32_e64 s[92:93], 16, v15
	v_sub_u32_e32 v15, v20, v41
	v_cmp_gt_u32_e64 s[54:55], 16, v27
	v_or_b32_e32 v27, 6, v20
	v_or_b32_e32 v20, 7, v20
	v_sub_u32_e32 v28, v27, v14
	v_sub_u32_e32 v14, v20, v14
	v_sub_u32_e32 v18, v18, v41
	v_sub_u32_e32 v23, v23, v41
	v_sub_u32_e32 v24, v24, v41
	v_sub_u32_e32 v25, v25, v41
	v_sub_u32_e32 v26, v26, v41
	v_sub_u32_e32 v27, v27, v41
	v_cmp_gt_u32_e64 s[70:71], 16, v14
	v_sub_u32_e32 v14, v20, v41
	v_max_i32_e32 v15, -15, v15
	v_max_i32_e32 v18, -15, v18
	v_max_i32_e32 v23, -15, v23
	v_max_i32_e32 v24, -15, v24
	v_max_i32_e32 v25, -15, v25
	v_max_i32_e32 v26, -15, v26
	v_max_i32_e32 v27, -15, v27
	v_max_i32_e32 v14, -15, v14
	v_add_u32_e32 v15, 15, v15
	v_add_u32_e32 v18, 15, v18
	v_add_u32_e32 v23, 15, v23
	v_add_u32_e32 v24, 15, v24
	v_add_u32_e32 v25, 15, v25
	v_add_u32_e32 v26, 15, v26
	v_add_u32_e32 v27, 15, v27
	v_add_u32_e32 v14, 15, v14
	v_min_u32_e32 v127, 30, v15
	v_min_u32_e32 v129, 30, v18
	v_min_u32_e32 v131, 30, v23
	v_min_u32_e32 v133, 30, v24
	v_min_u32_e32 v135, 30, v25
	v_min_u32_e32 v137, 30, v26
	v_min_u32_e32 v139, 30, v27
	v_min_u32_e32 v141, 30, v14
	v_lshlrev_b32_e32 v15, 2, v127
	v_readlane_b32 s1, v252, 23
	v_lshlrev_b32_e32 v18, 2, v129
	v_lshlrev_b32_e32 v23, 2, v131
	v_lshlrev_b32_e32 v24, 2, v133
	v_lshlrev_b32_e32 v25, 2, v135
	v_lshlrev_b32_e32 v26, 2, v137
	v_lshlrev_b32_e32 v27, 2, v139
	v_lshlrev_b32_e32 v14, 2, v141
	v_add_u32_e32 v128, s1, v15
	v_add_u32_e32 v130, s1, v18
	v_add_u32_e32 v132, s1, v23
	v_add_u32_e32 v134, s1, v24
	v_add_u32_e32 v136, s1, v25
	v_add_u32_e32 v138, s1, v26
	v_add_u32_e32 v140, s1, v27
	v_add_u32_e32 v142, s1, v14
	v_readlane_b32 s1, v252, 25
	v_lshlrev_b32_e32 v124, 4, v22
	v_and_b32_e32 v16, 6, v16
	v_add_u32_e32 v143, s1, v15
	v_add_u32_e32 v144, s1, v18
	v_add_u32_e32 v145, s1, v23
	v_add_u32_e32 v146, s1, v24
	v_add_u32_e32 v147, s1, v25
	v_add_u32_e32 v148, s1, v26
	v_add_u32_e32 v149, s1, v27
	v_add_u32_e32 v150, s1, v14
	v_readlane_b32 s1, v252, 26
	v_bfe_u32 v22, v10, 3, 1
	v_lshl_add_u64 v[100:101], s[64:65], 0, v[190:191]
	v_bitop3_b32 v14, v19, v17, s1 bitop3:0x36
	v_readlane_b32 s1, v252, 29
	v_lshlrev_b32_e32 v190, 4, v14
	v_lshl_add_u64 v[102:103], s[64:65], 0, v[190:191]
	v_bitop3_b32 v14, v19, v17, s1 bitop3:0x36
	v_lshlrev_b32_e32 v190, 4, v14
	v_bitop3_b32 v14, v16, v21, v22 bitop3:0x36
	v_lshlrev_b32_e32 v151, 4, v14
	v_or_b32_e32 v14, 2, v21
	v_bitop3_b32 v14, v16, v14, v22 bitop3:0x36
	s_movk_i32 s0, 0x1d1
	v_readlane_b32 s4, v252, 24
	v_lshlrev_b32_e32 v152, 4, v14
	v_or_b32_e32 v14, 4, v21
	v_cmp_gt_i32_e64 s[78:79], s0, v10
	s_mov_b32 s74, s6
	s_lshl_b32 s0, s6, 4
	v_lshl_add_u32 v123, v10, 2, s4
	v_bitop3_b32 v14, v16, v14, v22 bitop3:0x36
	v_readlane_b32 s4, v250, 12
	v_lshlrev_b32_e32 v153, 4, v14
	v_or_b32_e32 v14, 6, v21
	v_readlane_b32 s16, v250, 24
	v_readlane_b32 s17, v250, 25
	v_ashrrev_i32_e32 v11, 31, v10
	v_mul_u32_u24_e32 v12, 48, v12
	v_lshl_add_u64 v[104:105], s[64:65], 0, v[190:191]
	v_bitop3_b32 v14, v16, v14, v22 bitop3:0x36
	v_readlane_b32 s12, v250, 20
	v_readlane_b32 s13, v250, 21
	v_readlane_b32 s18, v250, 26
	v_readlane_b32 s19, v250, 27
	v_mov_b32_e32 v190, v191
	v_readlane_b32 s16, v252, 19
	v_bfe_u32 v122, v10, 3, 3
	v_cmp_gt_u32_e64 s[62:63], 16, v28
	v_lshlrev_b32_e32 v154, 4, v14
	v_lshl_add_u64 v[106:107], v[10:11], 2, s[12:13]
	v_lshl_add_u32 v155, v13, 7, 0
	v_add_u32_e32 v156, s22, v1
	v_mov_b64_e32 v[114:115], s[20:21]
	v_add_u32_e32 v157, 0, v12
	v_mov_b64_e32 v[108:109], v[190:191]
	v_mov_b64_e32 v[110:111], v[190:191]
	v_mov_b64_e32 v[112:113], v[190:191]
	v_mov_b64_e32 v[116:117], v[190:191]
	v_readlane_b32 s17, v252, 20
	v_readlane_b32 s18, v252, 21
	v_readlane_b32 s19, v252, 22
	v_readlane_b32 s20, v252, 32
	v_readlane_b32 s21, v252, 27
	v_readlane_b32 s23, v252, 34
	v_readlane_b32 s64, v252, 33
	v_readlane_b32 s65, v252, 35
	v_readlane_b32 s5, v250, 13
	v_readlane_b32 s6, v250, 14
	v_readlane_b32 s7, v250, 15
	v_readlane_b32 s8, v250, 16
	v_readlane_b32 s9, v250, 17
	v_readlane_b32 s10, v250, 18
	v_readlane_b32 s11, v250, 19
	v_readlane_b32 s14, v250, 22
	v_readlane_b32 s15, v250, 23
	s_branch .LBB0_286

; #define LAS __attribute__((address_space(3)))
; __device__ __forceinline__ void ph_na_mfma(const Args& a, const Frame& F, int l) {
;     ...
;             const int rs = min(max(r0 - 4, 0), R - 8);
; #pragma unroll
;             for (int i = 0; i < 16; ++i) { const int id = w * 16 + i, t = id >> 6, ri = (id >> 3) & 7, j8 = id & 7, row = rs + ri;
;                 const int colw = 8 * j8 + (lane >> 3);
;                 const bf16* gp = Z + ((size_t)((t ? 32 : 16) + h) * NTOK + (s0 + row * 64 + colw)) * 64 + (((lane & 7) ^ NA_SWZ(colw)) * 8);
;                 glds16_asm(gp, (unsigned)(size_t)(L + (t ? VR : KR) + (row % 9) * 8192 + j8 * 1024)); }
;             if (tid < 465) ((LAS float*)(L + BIAS))[tid] = a.in[I_RPB][((size_t)l * 16 + h) * 465 + tid];
.LBB0_290:
	v_sub_u32_e64 v1, s1, 4 clamp
	s_and_b32 s6, s6, 15
	s_add_i32 s36, s5, -8
	v_readfirstlane_b32 s7, v1
	s_min_u32 s7, s7, s36
	s_or_b32 s8, s6, s18
	s_mul_i32 s82, s8, 0xa000
	s_add_i32 s8, s7, s20
	v_add_u32_e32 v158, s4, v122
	s_lshl_b32 s9, s8, 6
	s_mul_i32 s10, s8, 57
	v_add_u32_e32 v10, s9, v158
	s_bfe_u32 s10, s10, 0x70009
	v_ashrrev_i32_e32 v11, 31, v10
	s_mul_i32 s10, s10, 9
	v_lshl_add_u64 v[10:11], v[10:11], 0, s[82:83]
	s_sub_i32 s8, s8, s10
	v_lshlrev_b64 v[10:11], 7, v[10:11]
	s_and_b32 s8, s8, 0xff
	v_lshl_add_u64 v[10:11], v[94:95], 0, v[10:11]
	s_lshl_b32 s8, s8, 13
	v_add_u32_e32 v1, 8, v158
	s_add_i32 s8, s19, s8
	s_mov_b32 s10, m0
	s_mov_b32 m0, s8
	s_nop 0
	global_load_lds_dwordx4 v[10:11], off nt
	s_mov_b32 m0, s10
	v_add_u32_e32 v10, s9, v1
	v_ashrrev_i32_e32 v11, 31, v10
	v_lshl_add_u64 v[10:11], v[10:11], 0, s[82:83]
	v_lshlrev_b64 v[10:11], 7, v[10:11]
	v_lshl_add_u64 v[10:11], v[96:97], 0, v[10:11]
	v_add_u32_e32 v12, 16, v158
	s_add_i32 s10, s8, 0x400
	s_mov_b32 s11, m0
	s_mov_b32 m0, s10
	s_nop 0
	global_load_lds_dwordx4 v[10:11], off nt
	s_mov_b32 m0, s11
	v_add_u32_e32 v10, s9, v12
	v_ashrrev_i32_e32 v11, 31, v10
	v_lshl_add_u64 v[10:11], v[10:11], 0, s[82:83]
	v_lshlrev_b64 v[10:11], 7, v[10:11]
	v_lshl_add_u64 v[10:11], v[98:99], 0, v[10:11]
	v_add_u32_e32 v13, 24, v158
	s_add_i32 s10, s8, 0x800
	s_mov_b32 s11, m0
	s_mov_b32 m0, s10
	s_nop 0
	global_load_lds_dwordx4 v[10:11], off nt
	s_mov_b32 m0, s11
	v_add_u32_e32 v10, s9, v13
	v_ashrrev_i32_e32 v11, 31, v10
	v_lshl_add_u64 v[10:11], v[10:11], 0, s[82:83]
	v_lshlrev_b64 v[10:11], 7, v[10:11]
	v_lshl_add_u64 v[10:11], v[100:101], 0, v[10:11]
	v_add_u32_e32 v14, 32, v158
	s_add_i32 s10, s8, 0xc00
	s_mov_b32 s11, m0
	s_mov_b32 m0, s10
	s_nop 0
	global_load_lds_dwordx4 v[10:11], off nt
	s_mov_b32 m0, s11
	v_add_u32_e32 v10, s9, v14
	v_ashrrev_i32_e32 v11, 31, v10
	v_lshl_add_u64 v[10:11], v[10:11], 0, s[82:83]
	v_lshlrev_b64 v[10:11], 7, v[10:11]
	v_lshl_add_u64 v[10:11], v[94:95], 0, v[10:11]
	v_add_u32_e32 v15, 40, v158
	s_add_i32 s10, s8, 0x1000
	s_mov_b32 s11, m0
	s_mov_b32 m0, s10
	s_nop 0
	global_load_lds_dwordx4 v[10:11], off nt
	s_mov_b32 m0, s11
	v_add_u32_e32 v10, s9, v15
	v_ashrrev_i32_e32 v11, 31, v10
	v_lshl_add_u64 v[10:11], v[10:11], 0, s[82:83]
	v_lshlrev_b64 v[10:11], 7, v[10:11]
	v_lshl_add_u64 v[10:11], v[96:97], 0, v[10:11]
	v_add_u32_e32 v16, 48, v158
	s_add_i32 s10, s8, 0x1400
	s_mov_b32 s11, m0
	s_mov_b32 m0, s10
	s_nop 0
	global_load_lds_dwordx4 v[10:11], off nt
	s_mov_b32 m0, s11
	v_add_u32_e32 v10, s9, v16
	v_ashrrev_i32_e32 v11, 31, v10
	v_lshl_add_u64 v[10:11], v[10:11], 0, s[82:83]
	v_lshlrev_b64 v[10:11], 7, v[10:11]
	v_lshl_add_u64 v[10:11], v[98:99], 0, v[10:11]
	v_add_u32_e32 v17, 56, v158
	s_add_i32 s10, s8, 0x1800
	s_mov_b32 s11, m0
	s_mov_b32 m0, s10
	s_nop 0
	global_load_lds_dwordx4 v[10:11], off nt
	s_mov_b32 m0, s11
	v_add_u32_e32 v10, s9, v17
	v_ashrrev_i32_e32 v11, 31, v10
	v_lshl_add_u64 v[10:11], v[10:11], 0, s[82:83]
	v_lshlrev_b64 v[10:11], 7, v[10:11]
	v_lshl_add_u64 v[10:11], v[100:101], 0, v[10:11]
	s_addk_i32 s8, 0x1c00
	s_mov_b32 s9, m0
	s_mov_b32 m0, s8
	s_nop 0
	global_load_lds_dwordx4 v[10:11], off nt
	s_mov_b32 m0, s9
	s_add_i32 s7, s7, s64
	s_lshl_b32 s8, s7, 6
	s_mul_i32 s9, s7, 57
	v_add_u32_e32 v10, s8, v158
	s_bfe_u32 s9, s9, 0x70009
	v_ashrrev_i32_e32 v11, 31, v10
	s_mul_i32 s9, s9, 9
	v_lshl_add_u64 v[10:11], v[10:11], 0, s[82:83]
	s_sub_i32 s7, s7, s9
	v_lshlrev_b64 v[10:11], 7, v[10:11]
	s_and_b32 s7, s7, 0xff
	v_lshl_add_u64 v[10:11], v[94:95], 0, v[10:11]
	s_lshl_b32 s7, s7, 13
	s_add_i32 s7, s19, s7
	s_mov_b32 s9, m0
	s_mov_b32 m0, s7
	s_nop 0
	global_load_lds_dwordx4 v[10:11], off nt
	s_mov_b32 m0, s9
	v_add_u32_e32 v10, s8, v1
	v_ashrrev_i32_e32 v11, 31, v10
	v_lshl_add_u64 v[10:11], v[10:11], 0, s[82:83]
	v_lshlrev_b64 v[10:11], 7, v[10:11]
	v_lshl_add_u64 v[10:11], v[96:97], 0, v[10:11]
	s_add_i32 s9, s7, 0x400
	s_mov_b32 s10, m0
	s_mov_b32 m0, s9
	s_nop 0
	global_load_lds_dwordx4 v[10:11], off nt
	s_mov_b32 m0, s10
	v_add_u32_e32 v10, s8, v12
	v_ashrrev_i32_e32 v11, 31, v10
	v_lshl_add_u64 v[10:11], v[10:11], 0, s[82:83]
	v_lshlrev_b64 v[10:11], 7, v[10:11]
	v_lshl_add_u64 v[10:11], v[98:99], 0, v[10:11]
	s_add_i32 s9, s7, 0x800
	s_mov_b32 s10, m0
	s_mov_b32 m0, s9
	s_nop 0
	global_load_lds_dwordx4 v[10:11], off nt
	s_mov_b32 m0, s10
	v_add_u32_e32 v10, s8, v13
	v_ashrrev_i32_e32 v11, 31, v10
	v_lshl_add_u64 v[10:11], v[10:11], 0, s[82:83]
	v_lshlrev_b64 v[10:11], 7, v[10:11]
	v_lshl_add_u64 v[10:11], v[100:101], 0, v[10:11]
	s_add_i32 s9, s7, 0xc00
	s_mov_b32 s10, m0
	s_mov_b32 m0, s9
	s_nop 0
	global_load_lds_dwordx4 v[10:11], off nt
	s_mov_b32 m0, s10
	v_add_u32_e32 v10, s8, v14
	v_ashrrev_i32_e32 v11, 31, v10
	v_lshl_add_u64 v[10:11], v[10:11], 0, s[82:83]
	v_lshlrev_b64 v[10:11], 7, v[10:11]
	v_lshl_add_u64 v[10:11], v[94:95], 0, v[10:11]
	s_add_i32 s9, s7, 0x1000
	s_mov_b32 s10, m0
	s_mov_b32 m0, s9
	s_nop 0
	global_load_lds_dwordx4 v[10:11], off nt
	s_mov_b32 m0, s10
	v_add_u32_e32 v10, s8, v15
	v_ashrrev_i32_e32 v11, 31, v10
	v_lshl_add_u64 v[10:11], v[10:11], 0, s[82:83]
	v_lshlrev_b64 v[10:11], 7, v[10:11]
	v_lshl_add_u64 v[10:11], v[96:97], 0, v[10:11]
	s_add_i32 s9, s7, 0x1400
	s_mov_b32 s10, m0
	s_mov_b32 m0, s9
	s_nop 0
	global_load_lds_dwordx4 v[10:11], off nt
	s_mov_b32 m0, s10
	v_add_u32_e32 v10, s8, v16
	v_ashrrev_i32_e32 v11, 31, v10
	v_lshl_add_u64 v[10:11], v[10:11], 0, s[82:83]
	v_lshlrev_b64 v[10:11], 7, v[10:11]
	v_lshl_add_u64 v[10:11], v[98:99], 0, v[10:11]
	s_add_i32 s9, s7, 0x1800
	s_mov_b32 s10, m0
	s_mov_b32 m0, s9
	s_nop 0
	global_load_lds_dwordx4 v[10:11], off nt
	s_mov_b32 m0, s10
	v_add_u32_e32 v10, s8, v17
	v_ashrrev_i32_e32 v11, 31, v10
	v_lshl_add_u64 v[10:11], v[10:11], 0, s[82:83]
	v_lshlrev_b64 v[10:11], 7, v[10:11]
	v_lshl_add_u64 v[10:11], v[100:101], 0, v[10:11]
	s_addk_i32 s7, 0x1c00
	s_mov_b32 s8, m0
	s_mov_b32 m0, s7
	s_nop 0
	global_load_lds_dwordx4 v[10:11], off nt
	s_mov_b32 m0, s8
	s_and_saveexec_b64 s[26:27], s[78:79]
	s_cbranch_execz .LBB0_292
	s_or_b32 s7, s6, s0
	s_mul_i32 s82, s7, 0x744
	v_lshl_add_u64 v[10:11], v[106:107], 0, s[82:83]
	global_load_dword v1, v[10:11], off
	s_waitcnt vmcnt(0)
	ds_write_b32 v123, v1

; #define NA_ITEM(it_, s0_, R_, h_, r_) do { if ((it_) < 2048) { const int _col = (it_) >> 5; r_ = (it_) & 31; R_ = 32; s0_ = (_col >> 4) * 2048; h_ = _col & 15; } \
;         else { const int _j = (it_) - 2048, _col = _j >> 8; r_ = _j & 255; R_ = 256; s0_ = 8192 + (_col >> 4) * 16384; h_ = _col & 15; } } while (0)
; #define NA_ROW_DMA(zoff_, row_, slotbase_) do { \
;         _Pragma("unroll") for (int _j = 0; _j < 2; ++_j) { const int _col = c0 + 8 * _j + (lane >> 3); \
;             const bf16* _gp = Z + ((size_t)((zoff_) / 64 + h) * NTOK + (s0 + (row_) * 64 + _col)) * 64 + (((lane & 7) ^ NA_SWZ(_col)) * 8); \
;             glds16_asm(_gp, (unsigned)(size_t)(L + (slotbase_) + (c0 + 8 * _j) * 128)); } } while (0)
; __device__ __forceinline__ void ph_na_mfma(const Args& a, const Frame& F, int l) {
;     ...
;             if (it + j + 1 < i1) {
;                 int s0n, Rn, hn, rn; NA_ITEM(it + j + 1, s0n, Rn, hn, rn);
;                 if (half == 0 && j + 1 < m) { const int rsn = min(max(rn - 4, 0), Rn - 8); if (rsn > rs) { NA_ROW_DMA(ZK, rsn + 7, KR + ((rsn + 7) % 9) * 8192); NA_ROW_DMA(ZV, rsn + 7, VR + ((rsn + 7) % 9) * 8192); } }
;                 const bf16* qp = Z + ((size_t)hn * NTOK + (s0n + rn * 64 + c)) * 64 + 8 * g; qn0 = *(const pg8::bf16x8*)qp; qn1 = *(const pg8::bf16x8*)(qp + 32);
;             }
.LBB0_366:
	s_cmp_ge_i32 s67, s37
	v_sub_u32_e64 v2, s4, 4 clamp
	s_cselect_b64 s[12:13], -1, 0
	s_xor_b64 s[14:15], s[16:17], -1
	v_readfirstlane_b32 s7, v2
	s_or_b64 s[12:13], s[14:15], s[12:13]
	s_min_u32 s7, s7, s10
	s_cmp_le_i32 s7, s9
	s_cselect_b64 s[10:11], -1, 0
	s_or_b64 s[10:11], s[12:13], s[10:11]
	s_and_b64 vcc, exec, s[10:11]
	s_cbranch_vccnz .LBB0_368
	s_add_i32 s7, s7, 7
	s_mul_i32 s10, s7, 57
	v_lshl_add_u32 v6, s7, 6, v158
	s_lshr_b32 s10, s10, 9
	s_mul_i32 s10, s10, 9
	v_add_u32_e32 v2, s22, v6
	s_sub_i32 s7, s7, s10
	v_ashrrev_i32_e32 v3, 31, v2
	s_and_b32 s7, s7, 0xff
	v_lshl_add_u64 v[4:5], v[2:3], 0, s[76:77]
	s_lshl_b32 s7, s7, 13
	v_lshlrev_b64 v[4:5], 7, v[4:5]
	s_add_i32 s7, s7, 0
	v_lshl_add_u64 v[4:5], v[102:103], 0, v[4:5]
	s_add_i32 s10, s7, s21
	s_mov_b32 s11, m0
	s_mov_b32 m0, s10
	s_nop 0
	global_load_lds_dwordx4 v[4:5], off nt
	s_mov_b32 m0, s11
	v_add_u32_e32 v4, s23, v6
	v_ashrrev_i32_e32 v5, 31, v4
	v_lshl_add_u64 v[6:7], v[4:5], 0, s[76:77]
	v_lshl_add_u64 v[2:3], v[2:3], 0, s[80:81]
	v_lshlrev_b64 v[6:7], 7, v[6:7]
	v_lshlrev_b64 v[2:3], 7, v[2:3]
	v_lshl_add_u64 v[6:7], v[104:105], 0, v[6:7]
	s_add_i32 s10, s7, s65
	s_mov_b32 s11, m0
	s_mov_b32 m0, s10
	s_nop 0
	global_load_lds_dwordx4 v[6:7], off nt
	s_mov_b32 m0, s11
	s_add_i32 s7, s7, 0x12000
	v_lshl_add_u64 v[2:3], v[102:103], 0, v[2:3]
	s_add_i32 s10, s7, s21
	s_mov_b32 s11, m0
	s_mov_b32 m0, s10
	s_nop 0
	global_load_lds_dwordx4 v[2:3], off nt
	s_mov_b32 m0, s11
	v_lshl_add_u64 v[2:3], v[4:5], 0, s[80:81]
	v_lshlrev_b64 v[2:3], 7, v[2:3]
	v_lshl_add_u64 v[2:3], v[104:105], 0, v[2:3]
	s_add_i32 s7, s7, s65
	s_mov_b32 s10, m0
	s_mov_b32 m0, s7
	s_nop 0
	global_load_lds_dwordx4 v[2:3], off nt
	s_mov_b32 m0, s10
.LBB0_368:
	v_lshl_or_b32 v2, s4, 6, v41
	s_and_b32 s5, s5, 15
	v_add_u32_e32 v2, s6, v2
	s_mul_i32 s82, s5, 0xa000
	v_ashrrev_i32_e32 v3, 31, v2
	v_lshl_add_u64 v[2:3], v[2:3], 0, s[82:83]
	v_lshlrev_b64 v[2:3], 7, v[2:3]
	v_lshl_add_u64 v[6:7], v[90:91], 0, v[2:3]
	global_load_dwordx4 v[2:5], v[6:7], off nt
	s_nop 0
	global_load_dwordx4 v[6:9], v[6:7], off offset:64 nt
